# HGRN inter-chunk QE operand: each ds_read2_b64 replaced by two ds_read_b64 (cheaper LDS-array cost per byte), counted lgkmcnt re-derived (v60 + rd2split)
# baseline (speedup 1.0000x reference)
.LBB0_950:
	v_lshlrev_b32_e32 v0, 1, v135
	v_lshlrev_b32_e32 v1, 1, v154
	v_add3_u32 v2, s62, v0, v1
	v_add_u32_e32 v207, s62, v63
	v_lshl_add_u32 v227, v54, 1, v207
	v_add_u32_e32 v0, v2, v176
	ds_read_b128 v[36:39], v2 offset:4352
	ds_read_b128 v[40:43], v2
	ds_read_b128 v[208:211], v2 offset:4416
	ds_read_b128 v[184:187], v2 offset:64
	ds_read_b128 v[212:215], v2 offset:4480
	ds_read_b128 v[228:231], v2 offset:128
	ds_read_b128 v[232:235], v2 offset:4544
	ds_read_b128 v[236:239], v2 offset:192
	ds_read_b64 v[188:189], v227 offset:14848
	ds_read_b64 v[240:241], v0
	ds_read_b64 v[242:243], v0 offset:32
	ds_read_b64 v[244:245], v0 offset:64
	ds_read_b64 v[246:247], v0 offset:96
	s_and_b64 s[12:13], s[54:55], s[52:53]
	v_mov_b32_e32 v190, v3
	v_mov_b32_e32 v191, v3
	s_waitcnt lgkmcnt(11)
	v_mfma_f32_16x16x32_bf16 v[36:39], v[36:39], v[40:43], 0
	s_waitcnt lgkmcnt(9)
	v_mfma_f32_16x16x32_bf16 v[36:39], v[208:211], v[184:187], v[36:39]
	s_waitcnt lgkmcnt(7)
	v_mfma_f32_16x16x32_bf16 v[36:39], v[212:215], v[228:231], v[36:39]
	s_waitcnt lgkmcnt(5)
	v_mfma_f32_16x16x32_bf16 v[36:39], v[232:235], v[236:239], v[36:39]
	ds_read_b64 v[208:209], v0 offset:128
	ds_read_b64 v[210:211], v0 offset:160
	ds_read_b64 v[212:213], v0 offset:192
	ds_read_b64 v[214:215], v0 offset:224
	v_cvt_pk_bf16_f32 v184, v4, v5
	v_cvt_pk_bf16_f32 v185, v6, v7
	v_cvt_pk_bf16_f32 v186, v8, v9
	v_cvt_pk_bf16_f32 v187, v10, v11
	v_mov_b32_e32 v2, v3
	s_nop 0
	v_cndmask_b32_e64 v192, v38, 0, s[12:13]
	s_and_b64 s[12:13], s[12:13], s[50:51]
	v_cndmask_b32_e64 v0, v37, 0, s[12:13]
	s_and_b64 s[12:13], s[12:13], s[48:49]
	v_cndmask_b32_e64 v36, v36, 0, s[12:13]
	v_cndmask_b32_e64 v1, v39, 0, s[54:55]
	v_cvt_pk_bf16_f32 v0, v36, v0
	v_cvt_pk_bf16_f32 v1, v192, v1
	s_nop 0
	s_waitcnt lgkmcnt(8)
	v_mfma_f32_16x16x32_bf16 v[36:39], v[188:191], v[0:3], 0
	v_cvt_pk_bf16_f32 v40, v12, v13
	v_cvt_pk_bf16_f32 v41, v14, v15
	v_cvt_pk_bf16_f32 v42, v16, v17
	v_cvt_pk_bf16_f32 v43, v18, v19
	v_cvt_pk_bf16_f32 v228, v20, v21
	v_cvt_pk_bf16_f32 v229, v22, v23
	v_cvt_pk_bf16_f32 v230, v24, v25
	v_cvt_pk_bf16_f32 v231, v26, v27
	v_cvt_pk_bf16_f32 v232, v28, v29
	v_cvt_pk_bf16_f32 v233, v30, v31
	v_cvt_pk_bf16_f32 v234, v32, v33
	v_cvt_pk_bf16_f32 v235, v34, v35
	s_waitcnt lgkmcnt(6)
	v_mfma_f32_16x16x32_bf16 v[36:39], v[184:187], v[240:243], v[36:39]
	s_waitcnt lgkmcnt(4)
	v_mfma_f32_16x16x32_bf16 v[36:39], v[40:43], v[244:247], v[36:39]
	s_waitcnt lgkmcnt(2)
	v_mfma_f32_16x16x32_bf16 v[36:39], v[228:231], v[208:211], v[36:39]
	s_waitcnt lgkmcnt(0)
	v_mfma_f32_16x16x32_bf16 v[36:39], v[232:235], v[212:215], v[36:39]
	v_add_u32_e32 v227, v207, v155
	v_add_u32_e32 v216, s62, v142
	v_add3_u32 v217, s62, v155, v156
	v_mov_b32_e32 v32, 0
	v_mov_b32_e32 v33, 0
	v_mov_b32_e32 v34, 0
	v_mov_b32_e32 v35, 0
	s_and_saveexec_b64 s[12:13], s[46:47]
	ds_read_b128 v[32:35], v227 offset:14848
	s_or_b64 exec, exec, s[12:13]
	ds_read_b64 v[240:241], v216 offset:20992
	ds_read_b128 v[184:187], v217 offset:8704
	ds_read_b128 v[40:43], v217 offset:9472
	ds_read_b128 v[228:231], v217 offset:10240
	ds_read_b128 v[232:235], v217 offset:11008
	s_ashr_i32 s12, s32, 4
	s_add_i32 s12, s12, -2
	v_sub_u32_e32 v0, v51, v54
	v_cvt_pk_bf16_f32 v192, v36, v37
	v_cvt_pk_bf16_f32 v193, v38, v39
	v_mad_i32_i24 v0, v0, s12, v197
	global_store_dwordx2 v0, v[192:193], s[100:101]
	s_waitcnt lgkmcnt(3)
	v_mul_f32_dpp v4, v240, v4 row_newbcast:0 row_mask:0xf bank_mask:0xf
	v_mul_f32_dpp v5, v241, v5 row_newbcast:0 row_mask:0xf bank_mask:0xf
	v_mul_f32_dpp v6, v240, v6 row_newbcast:1 row_mask:0xf bank_mask:0xf
	v_mul_f32_dpp v7, v241, v7 row_newbcast:1 row_mask:0xf bank_mask:0xf
	s_nop 1
	v_mfma_f32_16x16x32_bf16 v[4:7], v[184:187], v[32:35], v[4:7]
	ds_read_b128 v[184:187], v217 offset:11776
	s_waitcnt lgkmcnt(3)
	v_mul_f32_dpp v8, v240, v8 row_newbcast:2 row_mask:0xf bank_mask:0xf
	v_mul_f32_dpp v9, v241, v9 row_newbcast:2 row_mask:0xf bank_mask:0xf
	v_mul_f32_dpp v10, v240, v10 row_newbcast:3 row_mask:0xf bank_mask:0xf
	v_mul_f32_dpp v11, v241, v11 row_newbcast:3 row_mask:0xf bank_mask:0xf
	s_nop 1
	v_mfma_f32_16x16x32_bf16 v[8:11], v[40:43], v[32:35], v[8:11]
	ds_read_b128 v[40:43], v217 offset:12544
	s_waitcnt lgkmcnt(3)
	v_mul_f32_dpp v12, v240, v12 row_newbcast:4 row_mask:0xf bank_mask:0xf
	v_mul_f32_dpp v13, v241, v13 row_newbcast:4 row_mask:0xf bank_mask:0xf
	v_mul_f32_dpp v14, v240, v14 row_newbcast:5 row_mask:0xf bank_mask:0xf
	v_mul_f32_dpp v15, v241, v15 row_newbcast:5 row_mask:0xf bank_mask:0xf
	s_nop 1
	v_mfma_f32_16x16x32_bf16 v[12:15], v[228:231], v[32:35], v[12:15]
	ds_read_b128 v[228:231], v217 offset:13312
	s_waitcnt lgkmcnt(3)
	v_mul_f32_dpp v16, v240, v16 row_newbcast:6 row_mask:0xf bank_mask:0xf
	v_mul_f32_dpp v17, v241, v17 row_newbcast:6 row_mask:0xf bank_mask:0xf
	v_mul_f32_dpp v18, v240, v18 row_newbcast:7 row_mask:0xf bank_mask:0xf
	v_mul_f32_dpp v19, v241, v19 row_newbcast:7 row_mask:0xf bank_mask:0xf
	s_nop 1
	v_mfma_f32_16x16x32_bf16 v[16:19], v[232:235], v[32:35], v[16:19]
	ds_read_b128 v[232:235], v217 offset:14080
	s_waitcnt lgkmcnt(3)
	v_mul_f32_dpp v20, v240, v20 row_newbcast:8 row_mask:0xf bank_mask:0xf
	v_mul_f32_dpp v21, v241, v21 row_newbcast:8 row_mask:0xf bank_mask:0xf
	v_mul_f32_dpp v22, v240, v22 row_newbcast:9 row_mask:0xf bank_mask:0xf
	v_mul_f32_dpp v23, v241, v23 row_newbcast:9 row_mask:0xf bank_mask:0xf
	s_nop 1
	v_mfma_f32_16x16x32_bf16 v[20:23], v[184:187], v[32:35], v[20:23]
	s_waitcnt lgkmcnt(2)
	v_mul_f32_dpp v24, v240, v24 row_newbcast:10 row_mask:0xf bank_mask:0xf
	v_mul_f32_dpp v25, v241, v25 row_newbcast:10 row_mask:0xf bank_mask:0xf
	v_mul_f32_dpp v26, v240, v26 row_newbcast:11 row_mask:0xf bank_mask:0xf
	v_mul_f32_dpp v27, v241, v27 row_newbcast:11 row_mask:0xf bank_mask:0xf
	s_nop 1
	v_mfma_f32_16x16x32_bf16 v[24:27], v[40:43], v[32:35], v[24:27]
	s_waitcnt lgkmcnt(1)
	v_mul_f32_dpp v28, v240, v28 row_newbcast:12 row_mask:0xf bank_mask:0xf
	v_mul_f32_dpp v29, v241, v29 row_newbcast:12 row_mask:0xf bank_mask:0xf
	v_mul_f32_dpp v30, v240, v30 row_newbcast:13 row_mask:0xf bank_mask:0xf
	v_mul_f32_dpp v31, v241, v31 row_newbcast:13 row_mask:0xf bank_mask:0xf
	s_nop 1
	v_mfma_f32_16x16x32_bf16 v[28:31], v[228:231], v[32:35], v[28:31]
	s_waitcnt lgkmcnt(0)
	v_mul_f32_dpp v212, v240, v148 row_newbcast:14 row_mask:0xf bank_mask:0xf
	v_mul_f32_dpp v213, v241, v149 row_newbcast:14 row_mask:0xf bank_mask:0xf
	v_mul_f32_dpp v214, v240, v150 row_newbcast:15 row_mask:0xf bank_mask:0xf
	v_mul_f32_dpp v215, v241, v151 row_newbcast:15 row_mask:0xf bank_mask:0xf
	s_nop 1
	v_mfma_f32_16x16x32_bf16 v[32:35], v[232:235], v[32:35], v[212:215]
	v_add_u32_e32 v197, s32, v197
	v_add_u32_e32 v198, s32, v198
	v_add_u32_e32 v248, s32, v248
	v_add_u32_e32 v249, s32, v249
	v_lshl_add_u64 v[48:49], v[48:49], 0, v[46:47]
	s_add_i32 s60, s60, 16
	s_add_i32 s61, s61, 1
	s_cmpk_lg_i32 s60, 0x100
	s_barrier
	s_cbranch_scc1 .LBB0_943
	s_mov_b64 s[58:59], -1
	s_branch .LBB0_1005
.Lhc_alt_top:
	s_nop 2
	v_mov_b32_e32 v148, v32
	v_mov_b32_e32 v149, v33
	v_mov_b32_e32 v150, v34
	v_mov_b32_e32 v151, v35
	s_bitcmp1_b32 s61, 0
	s_cselect_b32 s62, 0x5800, 0
	v_lshlrev_b32_e32 v0, 1, v135
	v_lshlrev_b32_e32 v1, 1, v154
	v_add3_u32 v2, s62, v0, v1
	v_add_u32_e32 v207, s62, v63
	v_lshl_add_u32 v227, v54, 1, v207
	v_add_u32_e32 v0, v2, v176
	ds_read_b128 v[36:39], v2 offset:4352
	ds_read_b128 v[40:43], v2
	ds_read_b128 v[208:211], v2 offset:4416
	ds_read_b128 v[184:187], v2 offset:64
	ds_read_b128 v[212:215], v2 offset:4480
	ds_read_b128 v[228:231], v2 offset:128
	ds_read_b128 v[232:235], v2 offset:4544
	ds_read_b128 v[236:239], v2 offset:192
	ds_read_b64 v[188:189], v227 offset:14848
	ds_read_b64 v[240:241], v0
	ds_read_b64 v[242:243], v0 offset:32
	ds_read_b64 v[244:245], v0 offset:64
	ds_read_b64 v[246:247], v0 offset:96
	s_and_b64 s[12:13], s[54:55], s[52:53]
	v_mov_b32_e32 v190, v3
	v_mov_b32_e32 v191, v3
	s_waitcnt lgkmcnt(11)
	v_mfma_f32_16x16x32_bf16 v[36:39], v[36:39], v[40:43], 0
	s_waitcnt lgkmcnt(9)
	v_mfma_f32_16x16x32_bf16 v[36:39], v[208:211], v[184:187], v[36:39]
	s_waitcnt lgkmcnt(7)
	v_mfma_f32_16x16x32_bf16 v[36:39], v[212:215], v[228:231], v[36:39]
	s_waitcnt lgkmcnt(5)
	v_mfma_f32_16x16x32_bf16 v[36:39], v[232:235], v[236:239], v[36:39]
	ds_read_b64 v[208:209], v0 offset:128
	ds_read_b64 v[210:211], v0 offset:160
	ds_read_b64 v[212:213], v0 offset:192
	ds_read_b64 v[214:215], v0 offset:224
	v_cvt_pk_bf16_f32 v184, v4, v5
	v_cvt_pk_bf16_f32 v185, v6, v7
	v_cvt_pk_bf16_f32 v186, v8, v9
	v_cvt_pk_bf16_f32 v187, v10, v11
	v_mov_b32_e32 v2, v3
	s_nop 0
	v_cndmask_b32_e64 v192, v38, 0, s[12:13]
	s_and_b64 s[12:13], s[12:13], s[50:51]
	v_cndmask_b32_e64 v0, v37, 0, s[12:13]
	s_and_b64 s[12:13], s[12:13], s[48:49]
	v_cndmask_b32_e64 v36, v36, 0, s[12:13]
	v_cndmask_b32_e64 v1, v39, 0, s[54:55]
	v_cvt_pk_bf16_f32 v0, v36, v0
	v_cvt_pk_bf16_f32 v1, v192, v1
	s_nop 0
	s_waitcnt lgkmcnt(8)
	v_mfma_f32_16x16x32_bf16 v[36:39], v[188:191], v[0:3], 0
	v_cvt_pk_bf16_f32 v40, v12, v13
	v_cvt_pk_bf16_f32 v41, v14, v15
	v_cvt_pk_bf16_f32 v42, v16, v17
	v_cvt_pk_bf16_f32 v43, v18, v19
	v_cvt_pk_bf16_f32 v228, v20, v21
	v_cvt_pk_bf16_f32 v229, v22, v23
	v_cvt_pk_bf16_f32 v230, v24, v25
	v_cvt_pk_bf16_f32 v231, v26, v27
	v_cvt_pk_bf16_f32 v232, v28, v29
	v_cvt_pk_bf16_f32 v233, v30, v31
	v_cvt_pk_bf16_f32 v234, v32, v33
	v_cvt_pk_bf16_f32 v235, v34, v35
	s_waitcnt lgkmcnt(6)
	v_mfma_f32_16x16x32_bf16 v[36:39], v[184:187], v[240:243], v[36:39]
	s_waitcnt lgkmcnt(4)
	v_mfma_f32_16x16x32_bf16 v[36:39], v[40:43], v[244:247], v[36:39]
	s_waitcnt lgkmcnt(2)
	v_mfma_f32_16x16x32_bf16 v[36:39], v[228:231], v[208:211], v[36:39]
	s_waitcnt lgkmcnt(0)
	v_mfma_f32_16x16x32_bf16 v[36:39], v[232:235], v[212:215], v[36:39]
	v_add_u32_e32 v227, v207, v155
	v_add_u32_e32 v216, s62, v142
	v_add3_u32 v217, s62, v155, v156
	v_mov_b32_e32 v32, 0
	v_mov_b32_e32 v33, 0
	v_mov_b32_e32 v34, 0
	v_mov_b32_e32 v35, 0
	s_and_saveexec_b64 s[12:13], s[46:47]
	ds_read_b128 v[32:35], v227 offset:14848
	s_or_b64 exec, exec, s[12:13]
	ds_read_b64 v[240:241], v216 offset:20992
	ds_read_b128 v[184:187], v217 offset:8704
	ds_read_b128 v[40:43], v217 offset:9472
	ds_read_b128 v[228:231], v217 offset:10240
	ds_read_b128 v[232:235], v217 offset:11008
	s_ashr_i32 s12, s32, 4
	s_add_i32 s12, s12, -2
	v_sub_u32_e32 v0, v51, v54
	v_cvt_pk_bf16_f32 v192, v36, v37
	v_cvt_pk_bf16_f32 v193, v38, v39
	v_mad_i32_i24 v0, v0, s12, v197
	global_store_dwordx2 v0, v[192:193], s[100:101]
	s_waitcnt lgkmcnt(3)
	v_mul_f32_dpp v4, v240, v4 row_newbcast:0 row_mask:0xf bank_mask:0xf
	v_mul_f32_dpp v5, v241, v5 row_newbcast:0 row_mask:0xf bank_mask:0xf
	v_mul_f32_dpp v6, v240, v6 row_newbcast:1 row_mask:0xf bank_mask:0xf
	v_mul_f32_dpp v7, v241, v7 row_newbcast:1 row_mask:0xf bank_mask:0xf
	s_nop 1
	v_mfma_f32_16x16x32_bf16 v[4:7], v[184:187], v[32:35], v[4:7]
	ds_read_b128 v[184:187], v217 offset:11776
	s_waitcnt lgkmcnt(3)
	v_mul_f32_dpp v8, v240, v8 row_newbcast:2 row_mask:0xf bank_mask:0xf
	v_mul_f32_dpp v9, v241, v9 row_newbcast:2 row_mask:0xf bank_mask:0xf
	v_mul_f32_dpp v10, v240, v10 row_newbcast:3 row_mask:0xf bank_mask:0xf
	v_mul_f32_dpp v11, v241, v11 row_newbcast:3 row_mask:0xf bank_mask:0xf
	s_nop 1
	v_mfma_f32_16x16x32_bf16 v[8:11], v[40:43], v[32:35], v[8:11]
	ds_read_b128 v[40:43], v217 offset:12544
	s_waitcnt lgkmcnt(3)
	v_mul_f32_dpp v12, v240, v12 row_newbcast:4 row_mask:0xf bank_mask:0xf
	v_mul_f32_dpp v13, v241, v13 row_newbcast:4 row_mask:0xf bank_mask:0xf
	v_mul_f32_dpp v14, v240, v14 row_newbcast:5 row_mask:0xf bank_mask:0xf
	v_mul_f32_dpp v15, v241, v15 row_newbcast:5 row_mask:0xf bank_mask:0xf
	s_nop 1
	v_mfma_f32_16x16x32_bf16 v[12:15], v[228:231], v[32:35], v[12:15]
	ds_read_b128 v[228:231], v217 offset:13312
	s_waitcnt lgkmcnt(3)
	v_mul_f32_dpp v16, v240, v16 row_newbcast:6 row_mask:0xf bank_mask:0xf
	v_mul_f32_dpp v17, v241, v17 row_newbcast:6 row_mask:0xf bank_mask:0xf
	v_mul_f32_dpp v18, v240, v18 row_newbcast:7 row_mask:0xf bank_mask:0xf
	v_mul_f32_dpp v19, v241, v19 row_newbcast:7 row_mask:0xf bank_mask:0xf
	s_nop 1
	v_mfma_f32_16x16x32_bf16 v[16:19], v[232:235], v[32:35], v[16:19]
	ds_read_b128 v[232:235], v217 offset:14080
	s_waitcnt lgkmcnt(3)
	v_mul_f32_dpp v20, v240, v20 row_newbcast:8 row_mask:0xf bank_mask:0xf
	v_mul_f32_dpp v21, v241, v21 row_newbcast:8 row_mask:0xf bank_mask:0xf
	v_mul_f32_dpp v22, v240, v22 row_newbcast:9 row_mask:0xf bank_mask:0xf
	v_mul_f32_dpp v23, v241, v23 row_newbcast:9 row_mask:0xf bank_mask:0xf
	s_nop 1
	v_mfma_f32_16x16x32_bf16 v[20:23], v[184:187], v[32:35], v[20:23]
	s_waitcnt lgkmcnt(2)
	v_mul_f32_dpp v24, v240, v24 row_newbcast:10 row_mask:0xf bank_mask:0xf
	v_mul_f32_dpp v25, v241, v25 row_newbcast:10 row_mask:0xf bank_mask:0xf
	v_mul_f32_dpp v26, v240, v26 row_newbcast:11 row_mask:0xf bank_mask:0xf
	v_mul_f32_dpp v27, v241, v27 row_newbcast:11 row_mask:0xf bank_mask:0xf
	s_nop 1
	v_mfma_f32_16x16x32_bf16 v[24:27], v[40:43], v[32:35], v[24:27]
	s_waitcnt lgkmcnt(1)
	v_mul_f32_dpp v28, v240, v28 row_newbcast:12 row_mask:0xf bank_mask:0xf
	v_mul_f32_dpp v29, v241, v29 row_newbcast:12 row_mask:0xf bank_mask:0xf
	v_mul_f32_dpp v30, v240, v30 row_newbcast:13 row_mask:0xf bank_mask:0xf
	v_mul_f32_dpp v31, v241, v31 row_newbcast:13 row_mask:0xf bank_mask:0xf
	s_nop 1
	v_mfma_f32_16x16x32_bf16 v[28:31], v[228:231], v[32:35], v[28:31]
	s_waitcnt lgkmcnt(0)
	v_mul_f32_dpp v212, v240, v148 row_newbcast:14 row_mask:0xf bank_mask:0xf
	v_mul_f32_dpp v213, v241, v149 row_newbcast:14 row_mask:0xf bank_mask:0xf
	v_mul_f32_dpp v214, v240, v150 row_newbcast:15 row_mask:0xf bank_mask:0xf
	v_mul_f32_dpp v215, v241, v151 row_newbcast:15 row_mask:0xf bank_mask:0xf
	s_nop 1
	v_mfma_f32_16x16x32_bf16 v[32:35], v[232:235], v[32:35], v[212:215]
	s_cmp_gt_u32 s61, 14
	s_cbranch_scc1 .Lhc_alt_tail
	s_waitcnt vmcnt(1)
	v_mov_b32_e32 v44, v200
	v_mov_b32_e32 v42, v202
	v_mov_b32_e32 v40, v204
	v_mov_b32_e32 v38, v206
	v_mov_b32_e32 v45, v199
	v_mov_b32_e32 v43, v201
	v_mov_b32_e32 v41, v203
	v_mov_b32_e32 v39, v205
	v_mov_b64_e32 v[36:37], v[152:153]
	s_cmpk_eq_i32 s60, 0xe0
	s_cbranch_scc1 .Lhc_alt_947
	global_load_ushort v199, v197, s[24:25]
	global_load_ushort v200, v197, s[98:99]
	global_load_ushort v201, v198, s[24:25]
	global_load_ushort v202, v198, s[98:99]
	global_load_ushort v203, v248, s[24:25]
	global_load_ushort v204, v248, s[98:99]
	global_load_ushort v205, v249, s[24:25]
	global_load_ushort v206, v249, s[98:99]
	global_load_dwordx2 v[152:153], v[48:49], off

.LBB0_985:
	v_lshlrev_b32_e32 v0, 1, v135
	v_lshlrev_b32_e32 v1, 1, v154
	v_add3_u32 v2, s82, v0, v1
	v_add_u32_e32 v207, s82, v63
	v_lshl_add_u32 v227, v54, 1, v207
	v_add_u32_e32 v0, v2, v176
	ds_read_b128 v[36:39], v2 offset:4352
	ds_read_b128 v[40:43], v2
	ds_read_b128 v[208:211], v2 offset:4416
	ds_read_b128 v[184:187], v2 offset:64
	ds_read_b128 v[212:215], v2 offset:4480
	ds_read_b128 v[228:231], v2 offset:128
	ds_read_b128 v[232:235], v2 offset:4544
	ds_read_b128 v[236:239], v2 offset:192
	ds_read_b64 v[188:189], v227 offset:14848
	ds_read_b64 v[240:241], v0
	ds_read_b64 v[242:243], v0 offset:32
	ds_read_b64 v[244:245], v0 offset:64
	ds_read_b64 v[246:247], v0 offset:96
	s_and_b64 s[14:15], s[54:55], s[52:53]
	v_mov_b32_e32 v190, v3
	v_mov_b32_e32 v191, v3
	s_waitcnt lgkmcnt(11)
	v_mfma_f32_16x16x32_bf16 v[36:39], v[36:39], v[40:43], 0
	s_waitcnt lgkmcnt(9)
	v_mfma_f32_16x16x32_bf16 v[36:39], v[208:211], v[184:187], v[36:39]
	s_waitcnt lgkmcnt(7)
	v_mfma_f32_16x16x32_bf16 v[36:39], v[212:215], v[228:231], v[36:39]
	s_waitcnt lgkmcnt(5)
	v_mfma_f32_16x16x32_bf16 v[36:39], v[232:235], v[236:239], v[36:39]
	ds_read_b64 v[208:209], v0 offset:128
	ds_read_b64 v[210:211], v0 offset:160
	ds_read_b64 v[212:213], v0 offset:192
	ds_read_b64 v[214:215], v0 offset:224
	v_cvt_pk_bf16_f32 v184, v4, v5
	v_cvt_pk_bf16_f32 v185, v6, v7
	v_cvt_pk_bf16_f32 v186, v8, v9
	v_cvt_pk_bf16_f32 v187, v10, v11
	v_mov_b32_e32 v2, v3
	s_nop 0
	v_cndmask_b32_e64 v192, v38, 0, s[14:15]
	s_and_b64 s[14:15], s[14:15], s[50:51]
	v_cndmask_b32_e64 v0, v37, 0, s[14:15]
	s_and_b64 s[14:15], s[14:15], s[48:49]
	v_cndmask_b32_e64 v36, v36, 0, s[14:15]
	v_cndmask_b32_e64 v1, v39, 0, s[54:55]
	v_cvt_pk_bf16_f32 v0, v36, v0
	v_cvt_pk_bf16_f32 v1, v192, v1
	s_nop 0
	s_waitcnt lgkmcnt(8)
	v_mfma_f32_16x16x32_bf16 v[36:39], v[188:191], v[0:3], 0
	v_cvt_pk_bf16_f32 v40, v12, v13
	v_cvt_pk_bf16_f32 v41, v14, v15
	v_cvt_pk_bf16_f32 v42, v16, v17
	v_cvt_pk_bf16_f32 v43, v18, v19
	v_cvt_pk_bf16_f32 v228, v20, v21
	v_cvt_pk_bf16_f32 v229, v22, v23
	v_cvt_pk_bf16_f32 v230, v24, v25
	v_cvt_pk_bf16_f32 v231, v26, v27
	v_cvt_pk_bf16_f32 v232, v28, v29
	v_cvt_pk_bf16_f32 v233, v30, v31
	v_cvt_pk_bf16_f32 v234, v32, v33
	v_cvt_pk_bf16_f32 v235, v34, v35
	s_waitcnt lgkmcnt(6)
	v_mfma_f32_16x16x32_bf16 v[36:39], v[184:187], v[240:243], v[36:39]
	s_waitcnt lgkmcnt(4)
	v_mfma_f32_16x16x32_bf16 v[36:39], v[40:43], v[244:247], v[36:39]
	s_waitcnt lgkmcnt(2)
	v_mfma_f32_16x16x32_bf16 v[36:39], v[228:231], v[208:211], v[36:39]
	s_waitcnt lgkmcnt(0)
	v_mfma_f32_16x16x32_bf16 v[36:39], v[232:235], v[212:215], v[36:39]
	v_add_u32_e32 v227, v207, v155
	v_add_u32_e32 v216, s82, v142
	v_add3_u32 v217, s82, v155, v156
	v_mov_b32_e32 v44, 0
	v_mov_b32_e32 v45, 0
	v_mov_b32_e32 v46, 0
	v_mov_b32_e32 v47, 0
	s_and_saveexec_b64 s[14:15], s[46:47]
	ds_read_b128 v[44:47], v227 offset:14848
	s_or_b64 exec, exec, s[14:15]
	ds_read_b64 v[240:241], v216 offset:20992
	ds_read_b128 v[184:187], v217 offset:8704
	ds_read_b128 v[40:43], v217 offset:9472
	ds_read_b128 v[228:231], v217 offset:10240
	ds_read_b128 v[232:235], v217 offset:11008
	s_ashr_i32 s14, s32, 4
	s_add_i32 s14, s14, -2
	v_sub_u32_e32 v0, v51, v54
	v_cvt_pk_bf16_f32 v192, v36, v37
	v_cvt_pk_bf16_f32 v193, v38, v39
	v_mad_i32_i24 v0, v0, s14, v197
	global_store_dwordx2 v0, v[192:193], s[100:101]
	s_waitcnt lgkmcnt(3)
	v_mul_f32_dpp v4, v240, v4 row_newbcast:0 row_mask:0xf bank_mask:0xf
	v_mul_f32_dpp v5, v241, v5 row_newbcast:0 row_mask:0xf bank_mask:0xf
	v_mul_f32_dpp v6, v240, v6 row_newbcast:1 row_mask:0xf bank_mask:0xf
	v_mul_f32_dpp v7, v241, v7 row_newbcast:1 row_mask:0xf bank_mask:0xf
	s_nop 1
	v_mfma_f32_16x16x32_bf16 v[4:7], v[184:187], v[44:47], v[4:7]
	ds_read_b128 v[184:187], v217 offset:11776
	s_waitcnt lgkmcnt(3)
	v_mul_f32_dpp v8, v240, v8 row_newbcast:2 row_mask:0xf bank_mask:0xf
	v_mul_f32_dpp v9, v241, v9 row_newbcast:2 row_mask:0xf bank_mask:0xf
	v_mul_f32_dpp v10, v240, v10 row_newbcast:3 row_mask:0xf bank_mask:0xf
	v_mul_f32_dpp v11, v241, v11 row_newbcast:3 row_mask:0xf bank_mask:0xf
	s_nop 1
	v_mfma_f32_16x16x32_bf16 v[8:11], v[40:43], v[44:47], v[8:11]
	ds_read_b128 v[40:43], v217 offset:12544
	s_waitcnt lgkmcnt(3)
	v_mul_f32_dpp v12, v240, v12 row_newbcast:4 row_mask:0xf bank_mask:0xf
	v_mul_f32_dpp v13, v241, v13 row_newbcast:4 row_mask:0xf bank_mask:0xf
	v_mul_f32_dpp v14, v240, v14 row_newbcast:5 row_mask:0xf bank_mask:0xf
	v_mul_f32_dpp v15, v241, v15 row_newbcast:5 row_mask:0xf bank_mask:0xf
	s_nop 1
	v_mfma_f32_16x16x32_bf16 v[12:15], v[228:231], v[44:47], v[12:15]
	ds_read_b128 v[228:231], v217 offset:13312
	s_waitcnt lgkmcnt(3)
	v_mul_f32_dpp v16, v240, v16 row_newbcast:6 row_mask:0xf bank_mask:0xf
	v_mul_f32_dpp v17, v241, v17 row_newbcast:6 row_mask:0xf bank_mask:0xf
	v_mul_f32_dpp v18, v240, v18 row_newbcast:7 row_mask:0xf bank_mask:0xf
	v_mul_f32_dpp v19, v241, v19 row_newbcast:7 row_mask:0xf bank_mask:0xf
	s_nop 1
	v_mfma_f32_16x16x32_bf16 v[16:19], v[232:235], v[44:47], v[16:19]
	ds_read_b128 v[232:235], v217 offset:14080
	s_waitcnt lgkmcnt(3)
	v_mul_f32_dpp v20, v240, v20 row_newbcast:8 row_mask:0xf bank_mask:0xf
	v_mul_f32_dpp v21, v241, v21 row_newbcast:8 row_mask:0xf bank_mask:0xf
	v_mul_f32_dpp v22, v240, v22 row_newbcast:9 row_mask:0xf bank_mask:0xf
	v_mul_f32_dpp v23, v241, v23 row_newbcast:9 row_mask:0xf bank_mask:0xf
	s_nop 1
	v_mfma_f32_16x16x32_bf16 v[20:23], v[184:187], v[44:47], v[20:23]
	s_waitcnt lgkmcnt(2)
	v_mul_f32_dpp v24, v240, v24 row_newbcast:10 row_mask:0xf bank_mask:0xf
	v_mul_f32_dpp v25, v241, v25 row_newbcast:10 row_mask:0xf bank_mask:0xf
	v_mul_f32_dpp v26, v240, v26 row_newbcast:11 row_mask:0xf bank_mask:0xf
	v_mul_f32_dpp v27, v241, v27 row_newbcast:11 row_mask:0xf bank_mask:0xf
	s_nop 1
	v_mfma_f32_16x16x32_bf16 v[24:27], v[40:43], v[44:47], v[24:27]
	s_waitcnt lgkmcnt(1)
	v_mul_f32_dpp v28, v240, v28 row_newbcast:12 row_mask:0xf bank_mask:0xf
	v_mul_f32_dpp v29, v241, v29 row_newbcast:12 row_mask:0xf bank_mask:0xf
	v_mul_f32_dpp v30, v240, v30 row_newbcast:13 row_mask:0xf bank_mask:0xf
	v_mul_f32_dpp v31, v241, v31 row_newbcast:13 row_mask:0xf bank_mask:0xf
	s_nop 1
	v_mfma_f32_16x16x32_bf16 v[28:31], v[228:231], v[44:47], v[28:31]
	s_waitcnt lgkmcnt(0)
	v_mul_f32_dpp v32, v240, v32 row_newbcast:14 row_mask:0xf bank_mask:0xf
	v_mul_f32_dpp v33, v241, v33 row_newbcast:14 row_mask:0xf bank_mask:0xf
	v_mul_f32_dpp v34, v240, v34 row_newbcast:15 row_mask:0xf bank_mask:0xf
	v_mul_f32_dpp v35, v241, v35 row_newbcast:15 row_mask:0xf bank_mask:0xf
	s_nop 1
	v_mfma_f32_16x16x32_bf16 v[32:35], v[232:235], v[44:47], v[32:35]
	v_add_u32_e32 v197, s32, v197
	v_add_u32_e32 v198, s32, v198
	v_add_u32_e32 v178, s32, v178
	v_add_u32_e32 v179, s32, v179
	v_lshl_add_u64 v[150:151], v[150:151], 0, v[146:147]
	s_add_i32 s81, s81, 1
	s_add_i32 s62, s62, 16
	s_add_i32 s14, s80, s81
	s_cmp_eq_u32 s14, 2
	s_barrier
	s_cbranch_scc1 .LBB0_1003
	s_branch .LBB0_979
.Lhl_alt_top:
	s_bitcmp1_b32 s81, 0
	s_cselect_b32 s82, 0x5800, 0
	v_lshlrev_b32_e32 v0, 1, v135
	v_lshlrev_b32_e32 v1, 1, v154
	v_add3_u32 v2, s82, v0, v1
	v_add_u32_e32 v207, s82, v63
	v_lshl_add_u32 v227, v54, 1, v207
	v_add_u32_e32 v0, v2, v176
	ds_read_b128 v[36:39], v2 offset:4352
	ds_read_b128 v[40:43], v2
	ds_read_b128 v[208:211], v2 offset:4416
	ds_read_b128 v[184:187], v2 offset:64
	ds_read_b128 v[212:215], v2 offset:4480
	ds_read_b128 v[228:231], v2 offset:128
	ds_read_b128 v[232:235], v2 offset:4544
	ds_read_b128 v[236:239], v2 offset:192
	ds_read_b64 v[188:189], v227 offset:14848
	ds_read_b64 v[240:241], v0
	ds_read_b64 v[242:243], v0 offset:32
	ds_read_b64 v[244:245], v0 offset:64
	ds_read_b64 v[246:247], v0 offset:96
	s_and_b64 s[14:15], s[54:55], s[52:53]
	v_mov_b32_e32 v190, v3
	v_mov_b32_e32 v191, v3
	s_waitcnt lgkmcnt(11)
	v_mfma_f32_16x16x32_bf16 v[36:39], v[36:39], v[40:43], 0
	s_waitcnt lgkmcnt(9)
	v_mfma_f32_16x16x32_bf16 v[36:39], v[208:211], v[184:187], v[36:39]
	s_waitcnt lgkmcnt(7)
	v_mfma_f32_16x16x32_bf16 v[36:39], v[212:215], v[228:231], v[36:39]
	s_waitcnt lgkmcnt(5)
	v_mfma_f32_16x16x32_bf16 v[36:39], v[232:235], v[236:239], v[36:39]
	ds_read_b64 v[208:209], v0 offset:128
	ds_read_b64 v[210:211], v0 offset:160
	ds_read_b64 v[212:213], v0 offset:192
	ds_read_b64 v[214:215], v0 offset:224
	v_cvt_pk_bf16_f32 v184, v4, v5
	v_cvt_pk_bf16_f32 v185, v6, v7
	v_cvt_pk_bf16_f32 v186, v8, v9
	v_cvt_pk_bf16_f32 v187, v10, v11
	v_mov_b32_e32 v2, v3
	s_nop 0
	v_cndmask_b32_e64 v192, v38, 0, s[14:15]
	s_and_b64 s[14:15], s[14:15], s[50:51]
	v_cndmask_b32_e64 v0, v37, 0, s[14:15]
	s_and_b64 s[14:15], s[14:15], s[48:49]
	v_cndmask_b32_e64 v36, v36, 0, s[14:15]
	v_cndmask_b32_e64 v1, v39, 0, s[54:55]
	v_cvt_pk_bf16_f32 v0, v36, v0
	v_cvt_pk_bf16_f32 v1, v192, v1
	s_nop 0
	s_waitcnt lgkmcnt(8)
	v_mfma_f32_16x16x32_bf16 v[36:39], v[188:191], v[0:3], 0
	v_cvt_pk_bf16_f32 v40, v12, v13
	v_cvt_pk_bf16_f32 v41, v14, v15
	v_cvt_pk_bf16_f32 v42, v16, v17
	v_cvt_pk_bf16_f32 v43, v18, v19
	v_cvt_pk_bf16_f32 v228, v20, v21
	v_cvt_pk_bf16_f32 v229, v22, v23
	v_cvt_pk_bf16_f32 v230, v24, v25
	v_cvt_pk_bf16_f32 v231, v26, v27
	v_cvt_pk_bf16_f32 v232, v28, v29
	v_cvt_pk_bf16_f32 v233, v30, v31
	v_cvt_pk_bf16_f32 v234, v32, v33
	v_cvt_pk_bf16_f32 v235, v34, v35
	s_waitcnt lgkmcnt(6)
	v_mfma_f32_16x16x32_bf16 v[36:39], v[184:187], v[240:243], v[36:39]
	s_waitcnt lgkmcnt(4)
	v_mfma_f32_16x16x32_bf16 v[36:39], v[40:43], v[244:247], v[36:39]
	s_waitcnt lgkmcnt(2)
	v_mfma_f32_16x16x32_bf16 v[36:39], v[228:231], v[208:211], v[36:39]
	s_waitcnt lgkmcnt(0)
	v_mfma_f32_16x16x32_bf16 v[36:39], v[232:235], v[212:215], v[36:39]
	v_add_u32_e32 v227, v207, v155
	v_add_u32_e32 v216, s82, v142
	v_add3_u32 v217, s82, v155, v156
	v_mov_b32_e32 v44, 0
	v_mov_b32_e32 v45, 0
	v_mov_b32_e32 v46, 0
	v_mov_b32_e32 v47, 0
	s_and_saveexec_b64 s[14:15], s[46:47]
	ds_read_b128 v[44:47], v227 offset:14848
	s_or_b64 exec, exec, s[14:15]
	ds_read_b64 v[240:241], v216 offset:20992
	ds_read_b128 v[184:187], v217 offset:8704
	ds_read_b128 v[40:43], v217 offset:9472
	ds_read_b128 v[228:231], v217 offset:10240
	ds_read_b128 v[232:235], v217 offset:11008
	s_ashr_i32 s14, s32, 4
	s_add_i32 s14, s14, -2
	v_sub_u32_e32 v0, v51, v54
	v_cvt_pk_bf16_f32 v192, v36, v37
	v_cvt_pk_bf16_f32 v193, v38, v39
	v_mad_i32_i24 v0, v0, s14, v197
	global_store_dwordx2 v0, v[192:193], s[100:101]
	s_waitcnt lgkmcnt(3)
	v_mul_f32_dpp v4, v240, v4 row_newbcast:0 row_mask:0xf bank_mask:0xf
	v_mul_f32_dpp v5, v241, v5 row_newbcast:0 row_mask:0xf bank_mask:0xf
	v_mul_f32_dpp v6, v240, v6 row_newbcast:1 row_mask:0xf bank_mask:0xf
	v_mul_f32_dpp v7, v241, v7 row_newbcast:1 row_mask:0xf bank_mask:0xf
	s_nop 1
	v_mfma_f32_16x16x32_bf16 v[4:7], v[184:187], v[44:47], v[4:7]
	ds_read_b128 v[184:187], v217 offset:11776
	s_waitcnt lgkmcnt(3)
	v_mul_f32_dpp v8, v240, v8 row_newbcast:2 row_mask:0xf bank_mask:0xf
	v_mul_f32_dpp v9, v241, v9 row_newbcast:2 row_mask:0xf bank_mask:0xf
	v_mul_f32_dpp v10, v240, v10 row_newbcast:3 row_mask:0xf bank_mask:0xf
	v_mul_f32_dpp v11, v241, v11 row_newbcast:3 row_mask:0xf bank_mask:0xf
	s_nop 1
	v_mfma_f32_16x16x32_bf16 v[8:11], v[40:43], v[44:47], v[8:11]
	ds_read_b128 v[40:43], v217 offset:12544
	s_waitcnt lgkmcnt(3)
	v_mul_f32_dpp v12, v240, v12 row_newbcast:4 row_mask:0xf bank_mask:0xf
	v_mul_f32_dpp v13, v241, v13 row_newbcast:4 row_mask:0xf bank_mask:0xf
	v_mul_f32_dpp v14, v240, v14 row_newbcast:5 row_mask:0xf bank_mask:0xf
	v_mul_f32_dpp v15, v241, v15 row_newbcast:5 row_mask:0xf bank_mask:0xf
	s_nop 1
	v_mfma_f32_16x16x32_bf16 v[12:15], v[228:231], v[44:47], v[12:15]
	ds_read_b128 v[228:231], v217 offset:13312
	s_waitcnt lgkmcnt(3)
	v_mul_f32_dpp v16, v240, v16 row_newbcast:6 row_mask:0xf bank_mask:0xf
	v_mul_f32_dpp v17, v241, v17 row_newbcast:6 row_mask:0xf bank_mask:0xf
	v_mul_f32_dpp v18, v240, v18 row_newbcast:7 row_mask:0xf bank_mask:0xf
	v_mul_f32_dpp v19, v241, v19 row_newbcast:7 row_mask:0xf bank_mask:0xf
	s_nop 1
	v_mfma_f32_16x16x32_bf16 v[16:19], v[232:235], v[44:47], v[16:19]
	ds_read_b128 v[232:235], v217 offset:14080
	s_waitcnt lgkmcnt(3)
	v_mul_f32_dpp v20, v240, v20 row_newbcast:8 row_mask:0xf bank_mask:0xf
	v_mul_f32_dpp v21, v241, v21 row_newbcast:8 row_mask:0xf bank_mask:0xf
	v_mul_f32_dpp v22, v240, v22 row_newbcast:9 row_mask:0xf bank_mask:0xf
	v_mul_f32_dpp v23, v241, v23 row_newbcast:9 row_mask:0xf bank_mask:0xf
	s_nop 1
	v_mfma_f32_16x16x32_bf16 v[20:23], v[184:187], v[44:47], v[20:23]
	s_waitcnt lgkmcnt(2)
	v_mul_f32_dpp v24, v240, v24 row_newbcast:10 row_mask:0xf bank_mask:0xf
	v_mul_f32_dpp v25, v241, v25 row_newbcast:10 row_mask:0xf bank_mask:0xf
	v_mul_f32_dpp v26, v240, v26 row_newbcast:11 row_mask:0xf bank_mask:0xf
	v_mul_f32_dpp v27, v241, v27 row_newbcast:11 row_mask:0xf bank_mask:0xf
	s_nop 1
	v_mfma_f32_16x16x32_bf16 v[24:27], v[40:43], v[44:47], v[24:27]
	s_waitcnt lgkmcnt(1)
	v_mul_f32_dpp v28, v240, v28 row_newbcast:12 row_mask:0xf bank_mask:0xf
	v_mul_f32_dpp v29, v241, v29 row_newbcast:12 row_mask:0xf bank_mask:0xf
	v_mul_f32_dpp v30, v240, v30 row_newbcast:13 row_mask:0xf bank_mask:0xf
	v_mul_f32_dpp v31, v241, v31 row_newbcast:13 row_mask:0xf bank_mask:0xf
	s_nop 1
	v_mfma_f32_16x16x32_bf16 v[28:31], v[228:231], v[44:47], v[28:31]
	s_waitcnt lgkmcnt(0)
	v_mul_f32_dpp v32, v240, v32 row_newbcast:14 row_mask:0xf bank_mask:0xf
	v_mul_f32_dpp v33, v241, v33 row_newbcast:14 row_mask:0xf bank_mask:0xf
	v_mul_f32_dpp v34, v240, v34 row_newbcast:15 row_mask:0xf bank_mask:0xf
	v_mul_f32_dpp v35, v241, v35 row_newbcast:15 row_mask:0xf bank_mask:0xf
	s_nop 1
	v_mfma_f32_16x16x32_bf16 v[32:35], v[232:235], v[44:47], v[32:35]
	s_add_i32 s14, s81, -1
	s_cmp_ge_u32 s14, s61
	s_cbranch_scc1 .Lhl_alt_tail
	s_cmp_ge_u32 s81, s61
	s_waitcnt vmcnt(1)
	v_mov_b32_e32 v199, v157
	v_mov_b32_e32 v200, v159
	v_mov_b32_e32 v201, v161
	v_mov_b32_e32 v202, v163
	v_mov_b32_e32 v203, v166
	v_mov_b32_e32 v204, v167
	v_mov_b32_e32 v205, v168
	v_mov_b32_e32 v206, v169
	v_mov_b64_e32 v[148:149], v[164:165]
	s_cbranch_scc1 .Lhl_alt_982
	global_load_ushort v168, v197, s[12:13]
	global_load_ushort v169, v197, s[98:99]
	global_load_ushort v166, v198, s[12:13]
	global_load_ushort v167, v198, s[98:99]
	global_load_ushort v161, v178, s[12:13]
	global_load_ushort v163, v178, s[98:99]
	global_load_ushort v157, v179, s[12:13]
	global_load_ushort v159, v179, s[98:99]
	global_load_dwordx2 v[164:165], v[150:151], off
